# XB10: XB6 with the XCD-last L1 invalidate issued together with its L2 write-back (before the top-level atomic)
# baseline (speedup 1.0000x reference)
; __device__ __forceinline__ unsigned xb_add(unsigned* p, unsigned v) { return __hip_atomic_fetch_add(p, v, __ATOMIC_RELAXED, __HIP_MEMORY_SCOPE_AGENT); }
; __device__ __forceinline__ void xcd_barrier(const XcdBarrier& b) {
;     ...
;         if (old + 1u == (gen + 1u) * nloc) {
;             __builtin_amdgcn_fence(__ATOMIC_RELEASE, "agent");
;             asm volatile("s_waitcnt vmcnt(0)" ::: "memory");
;             const unsigned og = xb_add(&bar[XB_TOP], 1u);
.LBB0_426:
	s_andn2_saveexec_b64 s[6:7], s[6:7]
	s_cbranch_execz .LBB0_446
	s_mov_b64 s[6:7], exec
	buffer_wbl2 sc1
	buffer_inv sc1
	v_mov_b32_e32 v19, v2
	s_lshl_b32 s100, s40, 2
	s_add_u32 s100, s100, 0x82400
	s_add_u32 s100, s4, s100
	s_addc_u32 s101, s5, 0
	s_waitcnt lgkmcnt(0)
	s_waitcnt vmcnt(0)
	v_mbcnt_lo_u32_b32 v2, s6, 0
	v_mbcnt_hi_u32_b32 v2, s7, v2
	v_cmp_eq_u32_e32 vcc, 0, v2
	s_and_saveexec_b64 s[8:9], vcc
	s_cbranch_execz .LBB0_429
	s_bcnt1_i32_b64 s6, s[6:7]
	v_mov_b32_e32 v5, s6
	global_atomic_add v5, v197, v5, s[4:5] offset:1024 sc0

; __device__ __forceinline__ unsigned xb_add(unsigned* p, unsigned v) { return __hip_atomic_fetch_add(p, v, __ATOMIC_RELAXED, __HIP_MEMORY_SCOPE_AGENT); }
; __device__ __forceinline__ void xcd_barrier(const XcdBarrier& b) {
;     ...
;         if (old + 1u == (gen + 1u) * nloc) {
;             __builtin_amdgcn_fence(__ATOMIC_RELEASE, "agent");
;             asm volatile("s_waitcnt vmcnt(0)" ::: "memory");
;             const unsigned og = xb_add(&bar[XB_TOP], 1u);
.LBB0_668:
	s_andn2_saveexec_b64 s[4:5], s[4:5]
	s_cbranch_execz .LBB0_688
	s_mov_b64 s[4:5], exec
	buffer_wbl2 sc1
	buffer_inv sc1
	v_mov_b32_e32 v19, v2
	s_lshl_b32 s100, s40, 2
	s_add_u32 s100, s100, 0x82400
	s_add_u32 s100, s2, s100
	s_addc_u32 s101, s3, 0
	s_waitcnt lgkmcnt(0)
	s_waitcnt vmcnt(0)
	v_mbcnt_lo_u32_b32 v2, s4, 0
	v_mbcnt_hi_u32_b32 v2, s5, v2
	v_cmp_eq_u32_e32 vcc, 0, v2
	s_and_saveexec_b64 s[6:7], vcc
	s_cbranch_execz .LBB0_671
	s_bcnt1_i32_b64 s4, s[4:5]
	v_mov_b32_e32 v5, s4
	global_atomic_add v5, v197, v5, s[2:3] offset:1024 sc0

; __device__ __forceinline__ unsigned xb_ld(unsigned* p)              { return __hip_atomic_load(p, __ATOMIC_RELAXED, __HIP_MEMORY_SCOPE_AGENT); }
; __device__ __forceinline__ unsigned xb_add(unsigned* p, unsigned v) { return __hip_atomic_fetch_add(p, v, __ATOMIC_RELAXED, __HIP_MEMORY_SCOPE_AGENT); }
; #define XB_SPIN(cond, bar) do { unsigned _sp = 0; while (cond) { __builtin_amdgcn_s_sleep(1); \
;     if ((++_sp & 255u) == 0u) { if (xb_ld(&(bar)[XB_TMO])) break; if (_sp > XB_SPIN_CAP) { atomicAdd(&(bar)[XB_TMO], 1u); break; } } } } while (0)
; __device__ __forceinline__ void xcd_barrier(const XcdBarrier& b) {
;     ...
;         if (old + 1u == (gen + 1u) * nloc) {
;             __builtin_amdgcn_fence(__ATOMIC_RELEASE, "agent");
;             asm volatile("s_waitcnt vmcnt(0)" ::: "memory");
;             const unsigned og = xb_add(&bar[XB_TOP], 1u);
;             const unsigned tg = og / nx;
;             if (og + 1u == (tg + 1u) * nx) xb_add(&bar[XB_TOPGEN], 1u);
;             else XB_SPIN(xb_ld(&bar[XB_TOPGEN]) == tg, bar);
;             __builtin_amdgcn_fence(__ATOMIC_ACQUIRE, "agent");
;             xb_add(&bar[XB_XGEN(b.x)], 1u);
.LBB0_1181:
	s_andn2_saveexec_b64 s[6:7], s[6:7]
	s_cbranch_execz .LBB0_1201
	s_mov_b64 s[6:7], exec
	buffer_wbl2 sc1
	buffer_inv sc1
	v_mov_b32_e32 v19, v2
	s_lshl_b32 s100, s40, 2
	s_add_u32 s100, s100, 0x82400
	s_add_u32 s100, s4, s100
	s_addc_u32 s101, s5, 0
	s_waitcnt lgkmcnt(0)
	s_waitcnt vmcnt(0)
	v_mbcnt_lo_u32_b32 v2, s6, 0
	v_mbcnt_hi_u32_b32 v2, s7, v2
	v_cmp_eq_u32_e32 vcc, 0, v2
	s_and_saveexec_b64 s[14:15], vcc
	s_cbranch_execz .LBB0_1184
	s_bcnt1_i32_b64 s6, s[6:7]
	v_mov_b32_e32 v5, s6
	global_atomic_add v5, v197, v5, s[4:5] offset:1024 sc0
